# v31 plus: in-proj epilogue pass 1 issues its per-row-group RMSNorm scale LDS reads together (one wait) in both instances
# baseline (speedup 1.0000x reference)
.LBB0_188:
	ds_read_b32 v200, v174
	ds_read_b32 v201, v177
	ds_read_b32 v202, v180
	ds_read_b32 v203, v183
	ds_read_b32 v204, v186
	ds_read_b32 v205, v189
	ds_read_b32 v206, v192
	s_cmp_eq_u32 s1, 1
	s_cselect_b64 s[46:47], -1, 0
	s_cmp_lg_u32 s1, 1
	s_cselect_b64 s[22:23], -1, 0
	s_waitcnt lgkmcnt(0)
	v_mov_b32_e32 v6, v200
	v_mov_b32_e32 v7, v6
	s_mov_b64 s[76:77], -1
	s_and_b64 vcc, exec, s[22:23]
	v_pk_mul_f32 v[130:131], v[114:115], v[6:7]
	v_pk_mul_f32 v[126:127], v[110:111], v[6:7]
	s_cbranch_vccz .LBB0_190
	v_mov_b32_e32 v7, v6
	v_pk_mul_f32 v[132:133], v[116:117], v[6:7]
	v_pk_mul_f32 v[128:129], v[112:113], v[6:7]
	s_mov_b64 s[76:77], 0

.LBB0_196:
	v_mov_b32_e32 v6, v201
	s_mov_b64 s[76:77], -1
	s_and_b64 vcc, exec, s[22:23]
	v_mov_b32_e32 v7, v6
	v_pk_mul_f32 v[114:115], v[98:99], v[6:7]
	v_pk_mul_f32 v[110:111], v[94:95], v[6:7]
	s_cbranch_vccz .LBB0_198
	v_mov_b32_e32 v7, v6
	v_pk_mul_f32 v[116:117], v[100:101], v[6:7]
	v_pk_mul_f32 v[112:113], v[96:97], v[6:7]
	s_mov_b64 s[76:77], 0

.LBB0_204:
	v_mov_b32_e32 v6, v202
	s_mov_b64 s[76:77], -1
	s_and_b64 vcc, exec, s[22:23]
	v_mov_b32_e32 v7, v6
	v_pk_mul_f32 v[98:99], v[82:83], v[6:7]
	v_pk_mul_f32 v[94:95], v[78:79], v[6:7]
	s_cbranch_vccz .LBB0_206
	v_mov_b32_e32 v7, v6
	v_pk_mul_f32 v[100:101], v[84:85], v[6:7]
	v_pk_mul_f32 v[96:97], v[80:81], v[6:7]
	s_mov_b64 s[76:77], 0

.LBB0_212:
	v_mov_b32_e32 v6, v203
	s_mov_b64 s[76:77], -1
	s_and_b64 vcc, exec, s[22:23]
	v_mov_b32_e32 v7, v6
	v_pk_mul_f32 v[82:83], v[66:67], v[6:7]
	v_pk_mul_f32 v[78:79], v[62:63], v[6:7]
	s_cbranch_vccz .LBB0_214
	v_mov_b32_e32 v7, v6
	v_pk_mul_f32 v[84:85], v[68:69], v[6:7]
	v_pk_mul_f32 v[80:81], v[64:65], v[6:7]
	s_mov_b64 s[76:77], 0

.LBB0_220:
	v_mov_b32_e32 v6, v204
	s_mov_b64 s[76:77], -1
	s_and_b64 vcc, exec, s[22:23]
	v_mov_b32_e32 v7, v6
	v_pk_mul_f32 v[66:67], v[50:51], v[6:7]
	v_pk_mul_f32 v[62:63], v[46:47], v[6:7]
	s_cbranch_vccz .LBB0_222
	v_mov_b32_e32 v7, v6
	v_pk_mul_f32 v[68:69], v[52:53], v[6:7]
	v_pk_mul_f32 v[64:65], v[48:49], v[6:7]
	s_mov_b64 s[76:77], 0

.LBB0_228:
	v_mov_b32_e32 v6, v205
	s_mov_b64 s[76:77], -1
	s_and_b64 vcc, exec, s[22:23]
	v_mov_b32_e32 v7, v6
	v_pk_mul_f32 v[50:51], v[34:35], v[6:7]
	v_pk_mul_f32 v[46:47], v[30:31], v[6:7]
	s_cbranch_vccz .LBB0_230
	v_mov_b32_e32 v7, v6
	v_pk_mul_f32 v[52:53], v[36:37], v[6:7]
	v_pk_mul_f32 v[48:49], v[32:33], v[6:7]
	s_mov_b64 s[76:77], 0

.LBB0_236:
	v_mov_b32_e32 v6, v206
	s_mov_b64 s[76:77], -1
	s_and_b64 vcc, exec, s[22:23]
	v_mov_b32_e32 v7, v6
	v_pk_mul_f32 v[34:35], v[26:27], v[6:7]
	v_pk_mul_f32 v[30:31], v[2:3], v[6:7]
	s_cbranch_vccz .LBB0_238
	v_mov_b32_e32 v7, v6
	v_pk_mul_f32 v[36:37], v[28:29], v[6:7]
	v_pk_mul_f32 v[32:33], v[4:5], v[6:7]
	s_mov_b64 s[76:77], 0

.LBB0_909:
	ds_read_b32 v200, v172
	ds_read_b32 v201, v175
	ds_read_b32 v202, v178
	ds_read_b32 v203, v181
	ds_read_b32 v204, v184
	ds_read_b32 v205, v187
	ds_read_b32 v206, v190
	s_cmp_eq_u32 s5, 1
	s_cselect_b64 s[80:81], -1, 0
	s_cmp_lg_u32 s5, 1
	s_cselect_b64 s[24:25], -1, 0
	s_waitcnt lgkmcnt(0)
	v_mov_b32_e32 v6, v200
	v_mov_b32_e32 v7, v6
	s_mov_b64 s[82:83], -1
	s_and_b64 vcc, exec, s[24:25]
	v_pk_mul_f32 v[130:131], v[114:115], v[6:7]
	v_pk_mul_f32 v[126:127], v[110:111], v[6:7]
	s_cbranch_vccz .LBB0_911
	v_mov_b32_e32 v7, v6
	v_pk_mul_f32 v[132:133], v[116:117], v[6:7]
	v_pk_mul_f32 v[128:129], v[112:113], v[6:7]
	s_mov_b64 s[82:83], 0

.LBB0_917:
	v_mov_b32_e32 v6, v201
	s_mov_b64 s[82:83], -1
	s_and_b64 vcc, exec, s[24:25]
	v_mov_b32_e32 v7, v6
	v_pk_mul_f32 v[114:115], v[98:99], v[6:7]
	v_pk_mul_f32 v[110:111], v[94:95], v[6:7]
	s_cbranch_vccz .LBB0_919
	v_mov_b32_e32 v7, v6
	v_pk_mul_f32 v[116:117], v[100:101], v[6:7]
	v_pk_mul_f32 v[112:113], v[96:97], v[6:7]
	s_mov_b64 s[82:83], 0

.LBB0_925:
	v_mov_b32_e32 v6, v202
	s_mov_b64 s[82:83], -1
	s_and_b64 vcc, exec, s[24:25]
	v_mov_b32_e32 v7, v6
	v_pk_mul_f32 v[98:99], v[82:83], v[6:7]
	v_pk_mul_f32 v[94:95], v[78:79], v[6:7]
	s_cbranch_vccz .LBB0_927
	v_mov_b32_e32 v7, v6
	v_pk_mul_f32 v[100:101], v[84:85], v[6:7]
	v_pk_mul_f32 v[96:97], v[80:81], v[6:7]
	s_mov_b64 s[82:83], 0

.LBB0_933:
	v_mov_b32_e32 v6, v203
	s_mov_b64 s[82:83], -1
	s_and_b64 vcc, exec, s[24:25]
	v_mov_b32_e32 v7, v6
	v_pk_mul_f32 v[82:83], v[66:67], v[6:7]
	v_pk_mul_f32 v[78:79], v[62:63], v[6:7]
	s_cbranch_vccz .LBB0_935
	v_mov_b32_e32 v7, v6
	v_pk_mul_f32 v[84:85], v[68:69], v[6:7]
	v_pk_mul_f32 v[80:81], v[64:65], v[6:7]
	s_mov_b64 s[82:83], 0

.LBB0_941:
	v_mov_b32_e32 v6, v204
	s_mov_b64 s[82:83], -1
	s_and_b64 vcc, exec, s[24:25]
	v_mov_b32_e32 v7, v6
	v_pk_mul_f32 v[66:67], v[50:51], v[6:7]
	v_pk_mul_f32 v[62:63], v[46:47], v[6:7]
	s_cbranch_vccz .LBB0_943
	v_mov_b32_e32 v7, v6
	v_pk_mul_f32 v[68:69], v[52:53], v[6:7]
	v_pk_mul_f32 v[64:65], v[48:49], v[6:7]
	s_mov_b64 s[82:83], 0

.LBB0_949:
	v_mov_b32_e32 v6, v205
	s_mov_b64 s[82:83], -1
	s_and_b64 vcc, exec, s[24:25]
	v_mov_b32_e32 v7, v6
	v_pk_mul_f32 v[50:51], v[34:35], v[6:7]
	v_pk_mul_f32 v[46:47], v[30:31], v[6:7]
	s_cbranch_vccz .LBB0_951
	v_mov_b32_e32 v7, v6
	v_pk_mul_f32 v[52:53], v[36:37], v[6:7]
	v_pk_mul_f32 v[48:49], v[32:33], v[6:7]
	s_mov_b64 s[82:83], 0

.LBB0_957:
	v_mov_b32_e32 v6, v206
	s_mov_b64 s[82:83], -1
	s_and_b64 vcc, exec, s[24:25]
	v_mov_b32_e32 v7, v6
	v_pk_mul_f32 v[34:35], v[26:27], v[6:7]
	v_pk_mul_f32 v[30:31], v[2:3], v[6:7]
	s_cbranch_vccz .LBB0_959
	v_mov_b32_e32 v7, v6
	v_pk_mul_f32 v[36:37], v[28:29], v[6:7]
	v_pk_mul_f32 v[32:33], v[4:5], v[6:7]
	s_mov_b64 s[82:83], 0
